# r41 + gmlp causal-dot tail loops: unroll x2, hoist 12 LDS reads per iteration with counted lgkm waits (same fmac order)
# speedup vs baseline: 1.0080x; 1.0023x over previous
.LBB0_510:
	v_add_u32_e32 v197, 0x12800, v2
	ds_read_b128 v[200:203], v197
	ds_read2st64_b32 v[216:217], v3 offset1:1
	ds_read2st64_b32 v[218:219], v3 offset0:2 offset1:3
	ds_read_b128 v[204:207], v197 offset:16
	ds_read2st64_b32 v[220:221], v3 offset0:4 offset1:5
	ds_read2st64_b32 v[222:223], v3 offset0:6 offset1:7
	ds_read_b128 v[208:211], v197 offset:32
	ds_read2st64_b32 v[224:225], v3 offset0:8 offset1:9
	ds_read2st64_b32 v[226:227], v3 offset0:10 offset1:11
	ds_read_b128 v[212:215], v197 offset:48
	ds_read2st64_b32 v[228:229], v3 offset0:12 offset1:13
	ds_read2st64_b32 v[230:231], v3 offset0:14 offset1:15
	s_add_i32 s0, s0, -16
	v_add_u32_e32 v3, 0x1000, v3
	v_add_u32_e32 v2, 64, v2
	s_cmp_eq_u32 s0, 0
	s_waitcnt lgkmcnt(10)
	v_fmac_f32_e32 v8, v200, v216
	v_fmac_f32_e32 v8, v201, v217
	s_waitcnt lgkmcnt(9)
	v_fmac_f32_e32 v8, v202, v218
	v_fmac_f32_e32 v8, v203, v219
	s_waitcnt lgkmcnt(7)
	v_fmac_f32_e32 v8, v204, v220
	v_fmac_f32_e32 v8, v205, v221
	s_waitcnt lgkmcnt(6)
	v_fmac_f32_e32 v8, v206, v222
	v_fmac_f32_e32 v8, v207, v223
	s_waitcnt lgkmcnt(4)
	v_fmac_f32_e32 v8, v208, v224
	v_fmac_f32_e32 v8, v209, v225
	s_waitcnt lgkmcnt(3)
	v_fmac_f32_e32 v8, v210, v226
	v_fmac_f32_e32 v8, v211, v227
	s_waitcnt lgkmcnt(1)
	v_fmac_f32_e32 v8, v212, v228
	v_fmac_f32_e32 v8, v213, v229
	s_waitcnt lgkmcnt(0)
	v_fmac_f32_e32 v8, v214, v230
	v_fmac_f32_e32 v8, v215, v231
	s_cbranch_scc0 .LBB0_510
	s_lshl_b32 s0, s21, 7
	v_lshlrev_b32_e32 v7, 2, v49
	s_add_i32 s88, s22, s0
	v_lshlrev_b32_e32 v2, 2, v48
	v_mov_b32_e32 v3, v0
	v_add_u32_e32 v4, s20, v7
	s_movk_i32 s0, 0x7f
	v_lshl_add_u64 v[2:3], s[66:67], 0, v[2:3]
	v_cmp_gt_i32_e32 vcc, s0, v4
	s_and_saveexec_b64 s[0:1], vcc
	s_cbranch_execz .LBB0_513
	v_ashrrev_i32_e32 v5, 31, v4
	v_lshl_add_u64 v[4:5], v[4:5], 0, s[88:89]
	v_lshlrev_b64 v[4:5], 8, v[4:5]
	v_lshl_add_u64 v[4:5], v[2:3], 0, v[4:5]
	global_store_dword v[4:5], v8, off

.LBB0_514:
	v_add_u32_e32 v197, 0x12900, v4
	ds_read_b128 v[200:203], v197
	ds_read2st64_b32 v[216:217], v5 offset1:1
	ds_read2st64_b32 v[218:219], v5 offset0:2 offset1:3
	ds_read_b128 v[204:207], v197 offset:16
	ds_read2st64_b32 v[220:221], v5 offset0:4 offset1:5
	ds_read2st64_b32 v[222:223], v5 offset0:6 offset1:7
	ds_read_b128 v[208:211], v197 offset:32
	ds_read2st64_b32 v[224:225], v5 offset0:8 offset1:9
	ds_read2st64_b32 v[226:227], v5 offset0:10 offset1:11
	ds_read_b128 v[212:215], v197 offset:48
	ds_read2st64_b32 v[228:229], v5 offset0:12 offset1:13
	ds_read2st64_b32 v[230:231], v5 offset0:14 offset1:15
	s_add_i32 s0, s0, -16
	v_add_u32_e32 v5, 0x1000, v5
	v_add_u32_e32 v4, 64, v4
	s_cmp_lg_u32 s0, 0
	s_waitcnt lgkmcnt(10)
	v_fmac_f32_e32 v8, v200, v216
	v_fmac_f32_e32 v8, v201, v217
	s_waitcnt lgkmcnt(9)
	v_fmac_f32_e32 v8, v202, v218
	v_fmac_f32_e32 v8, v203, v219
	s_waitcnt lgkmcnt(7)
	v_fmac_f32_e32 v8, v204, v220
	v_fmac_f32_e32 v8, v205, v221
	s_waitcnt lgkmcnt(6)
	v_fmac_f32_e32 v8, v206, v222
	v_fmac_f32_e32 v8, v207, v223
	s_waitcnt lgkmcnt(4)
	v_fmac_f32_e32 v8, v208, v224
	v_fmac_f32_e32 v8, v209, v225
	s_waitcnt lgkmcnt(3)
	v_fmac_f32_e32 v8, v210, v226
	v_fmac_f32_e32 v8, v211, v227
	s_waitcnt lgkmcnt(1)
	v_fmac_f32_e32 v8, v212, v228
	v_fmac_f32_e32 v8, v213, v229
	s_waitcnt lgkmcnt(0)
	v_fmac_f32_e32 v8, v214, v230
	v_fmac_f32_e32 v8, v215, v231
	s_cbranch_scc1 .LBB0_514
	v_add3_u32 v4, s20, v7, 1
	s_movk_i32 s0, 0x7f
	v_cmp_gt_i32_e32 vcc, s0, v4
	s_and_saveexec_b64 s[0:1], vcc
	s_cbranch_execz .LBB0_517
	v_ashrrev_i32_e32 v5, 31, v4
	v_lshl_add_u64 v[4:5], v[4:5], 0, s[88:89]
	v_lshlrev_b64 v[4:5], 8, v[4:5]
	v_lshl_add_u64 v[4:5], v[2:3], 0, v[4:5]
	global_store_dword v[4:5], v8, off

.LBB0_518:
	v_add_u32_e32 v197, 0x12a00, v4
	ds_read_b128 v[200:203], v197
	ds_read2st64_b32 v[216:217], v5 offset1:1
	ds_read2st64_b32 v[218:219], v5 offset0:2 offset1:3
	ds_read_b128 v[204:207], v197 offset:16
	ds_read2st64_b32 v[220:221], v5 offset0:4 offset1:5
	ds_read2st64_b32 v[222:223], v5 offset0:6 offset1:7
	ds_read_b128 v[208:211], v197 offset:32
	ds_read2st64_b32 v[224:225], v5 offset0:8 offset1:9
	ds_read2st64_b32 v[226:227], v5 offset0:10 offset1:11
	ds_read_b128 v[212:215], v197 offset:48
	ds_read2st64_b32 v[228:229], v5 offset0:12 offset1:13
	ds_read2st64_b32 v[230:231], v5 offset0:14 offset1:15
	s_add_i32 s0, s0, -16
	v_add_u32_e32 v5, 0x1000, v5
	v_add_u32_e32 v4, 64, v4
	s_cmp_lg_u32 s0, 0
	s_waitcnt lgkmcnt(10)
	v_fmac_f32_e32 v8, v200, v216
	v_fmac_f32_e32 v8, v201, v217
	s_waitcnt lgkmcnt(9)
	v_fmac_f32_e32 v8, v202, v218
	v_fmac_f32_e32 v8, v203, v219
	s_waitcnt lgkmcnt(7)
	v_fmac_f32_e32 v8, v204, v220
	v_fmac_f32_e32 v8, v205, v221
	s_waitcnt lgkmcnt(6)
	v_fmac_f32_e32 v8, v206, v222
	v_fmac_f32_e32 v8, v207, v223
	s_waitcnt lgkmcnt(4)
	v_fmac_f32_e32 v8, v208, v224
	v_fmac_f32_e32 v8, v209, v225
	s_waitcnt lgkmcnt(3)
	v_fmac_f32_e32 v8, v210, v226
	v_fmac_f32_e32 v8, v211, v227
	s_waitcnt lgkmcnt(1)
	v_fmac_f32_e32 v8, v212, v228
	v_fmac_f32_e32 v8, v213, v229
	s_waitcnt lgkmcnt(0)
	v_fmac_f32_e32 v8, v214, v230
	v_fmac_f32_e32 v8, v215, v231
	s_cbranch_scc1 .LBB0_518
	v_add3_u32 v4, s20, v7, 2
	s_movk_i32 s0, 0x7f
	v_cmp_gt_i32_e32 vcc, s0, v4
	s_and_saveexec_b64 s[0:1], vcc
	s_cbranch_execz .LBB0_521
	v_ashrrev_i32_e32 v5, 31, v4
	v_lshl_add_u64 v[4:5], v[4:5], 0, s[88:89]
	v_lshlrev_b64 v[4:5], 8, v[4:5]
	v_lshl_add_u64 v[4:5], v[2:3], 0, v[4:5]
	global_store_dword v[4:5], v8, off

.LBB0_522:
	v_add_u32_e32 v197, 0x12b00, v1
	ds_read_b128 v[200:203], v197
	ds_read2st64_b32 v[216:217], v6 offset1:1
	ds_read2st64_b32 v[218:219], v6 offset0:2 offset1:3
	ds_read_b128 v[204:207], v197 offset:16
	ds_read2st64_b32 v[220:221], v6 offset0:4 offset1:5
	ds_read2st64_b32 v[222:223], v6 offset0:6 offset1:7
	ds_read_b128 v[208:211], v197 offset:32
	ds_read2st64_b32 v[224:225], v6 offset0:8 offset1:9
	ds_read2st64_b32 v[226:227], v6 offset0:10 offset1:11
	ds_read_b128 v[212:215], v197 offset:48
	ds_read2st64_b32 v[228:229], v6 offset0:12 offset1:13
	ds_read2st64_b32 v[230:231], v6 offset0:14 offset1:15
	s_add_i32 s0, s0, -16
	v_add_u32_e32 v6, 0x1000, v6
	v_add_u32_e32 v1, 64, v1
	s_cmp_lg_u32 s0, 0
	s_waitcnt lgkmcnt(10)
	v_fmac_f32_e32 v8, v200, v216
	v_fmac_f32_e32 v8, v201, v217
	s_waitcnt lgkmcnt(9)
	v_fmac_f32_e32 v8, v202, v218
	v_fmac_f32_e32 v8, v203, v219
	s_waitcnt lgkmcnt(7)
	v_fmac_f32_e32 v8, v204, v220
	v_fmac_f32_e32 v8, v205, v221
	s_waitcnt lgkmcnt(6)
	v_fmac_f32_e32 v8, v206, v222
	v_fmac_f32_e32 v8, v207, v223
	s_waitcnt lgkmcnt(4)
	v_fmac_f32_e32 v8, v208, v224
	v_fmac_f32_e32 v8, v209, v225
	s_waitcnt lgkmcnt(3)
	v_fmac_f32_e32 v8, v210, v226
	v_fmac_f32_e32 v8, v211, v227
	s_waitcnt lgkmcnt(1)
	v_fmac_f32_e32 v8, v212, v228
	v_fmac_f32_e32 v8, v213, v229
	s_waitcnt lgkmcnt(0)
	v_fmac_f32_e32 v8, v214, v230
	v_fmac_f32_e32 v8, v215, v231
	s_cbranch_scc1 .LBB0_522
	v_add3_u32 v4, s20, v7, 3
	s_movk_i32 s0, 0x7f
	v_cmp_gt_i32_e32 vcc, s0, v4
	s_and_saveexec_b64 s[0:1], vcc
	s_cbranch_execz .LBB0_525
	v_ashrrev_i32_e32 v5, 31, v4
	v_lshl_add_u64 v[4:5], v[4:5], 0, s[88:89]
	v_lshlrev_b64 v[4:5], 8, v[4:5]
	v_lshl_add_u64 v[2:3], v[2:3], 0, v[4:5]
	global_store_dword v[2:3], v8, off
